# UP GEMM: mid-K gate hook and epilogue gate loads batched (second half issued early into dead fragment registers): one round trip instead of two in each
# baseline (speedup 1.0000x reference)
.LBB0_132:
	v_mov_b32_e32 v1, v192
	v_mov_b32_e32 v2, v169
	s_mov_b64 s[48:49], 0x10000
	v_add_u32_e32 v132, vcc_lo, v1
	v_ashrrev_i32_e32 v133, 31, v132
	v_lshl_add_u32 v2, v2, 3, s99
	v_lshlrev_b64 v[132:133], 12, v[132:133]
	v_ashrrev_i32_e32 v3, 31, v2
	v_lshl_add_u64 v[132:133], s[10:11], 0, v[132:133]
	v_lshl_add_u64 v[2:3], v[2:3], 1, v[132:133]
	global_load_dwordx4 v[132:135], v[2:3], off offset:2048
	global_load_dwordx4 v[136:139], v[2:3], off offset:2304
	v_lshl_add_u64 v[144:145], v[2:3], 0, s[48:49]
	global_load_dwordx4 v[140:143], v[144:145], off offset:2048
	s_nop 0
	global_load_dwordx4 v[144:147], v[144:145], off offset:2304
	s_mov_b64 s[48:49], 0x20000
	v_lshl_add_u64 v[182:183], v[2:3], 0, s[48:49]
	global_load_dwordx4 v[148:151], v[182:183], off offset:2048
	s_nop 0
	global_load_dwordx4 v[182:185], v[182:183], off offset:2304
	s_mov_b64 s[48:49], 0x30000
	v_lshl_add_u64 v[190:191], v[2:3], 0, s[48:49]
	global_load_dwordx4 v[186:189], v[190:191], off offset:2048
	global_load_dwordx4 v[196:199], v[190:191], off offset:2304
	s_mov_b64 s[48:49], 0x80000
	v_lshl_add_u64 v[244:245], v[2:3], 0, s[48:49]
	global_load_dwordx4 v[212:215], v[244:245], off offset:2048
	global_load_dwordx4 v[216:219], v[244:245], off offset:2304
	s_mov_b64 s[48:49], 0x90000
	v_lshl_add_u64 v[246:247], v[2:3], 0, s[48:49]
	global_load_dwordx4 v[220:223], v[246:247], off offset:2048
	global_load_dwordx4 v[224:227], v[246:247], off offset:2304
	s_mov_b64 s[48:49], 0xa0000
	v_lshl_add_u64 v[248:249], v[2:3], 0, s[48:49]
	global_load_dwordx4 v[228:231], v[248:249], off offset:2048
	global_load_dwordx4 v[232:235], v[248:249], off offset:2304
	s_mov_b64 s[48:49], 0xb0000
	v_lshl_add_u64 v[250:251], v[2:3], 0, s[48:49]
	global_load_dwordx4 v[236:239], v[250:251], off offset:2048
	global_load_dwordx4 v[240:243], v[250:251], off offset:2304
	s_mov_b64 s[48:49], 0x80000
	s_waitcnt vmcnt(8)
	v_lshlrev_b32_e32 v190, 16, v132
	v_and_b32_e32 v191, 0xffff0000, v132
	v_lshlrev_b32_e32 v132, 16, v133
	v_and_b32_e32 v133, 0xffff0000, v133
	v_lshlrev_b32_e32 v208, 16, v134
	v_and_b32_e32 v209, 0xffff0000, v134
	v_lshlrev_b32_e32 v134, 16, v135
	v_and_b32_e32 v135, 0xffff0000, v135
	v_pk_mul_f32 v[126:127], v[126:127], v[132:133]
	v_lshlrev_b32_e32 v132, 16, v136
	v_and_b32_e32 v133, 0xffff0000, v136
	v_pk_mul_f32 v[130:131], v[130:131], v[134:135]
	v_lshlrev_b32_e32 v134, 16, v137
	v_and_b32_e32 v135, 0xffff0000, v137
	v_pk_mul_f32 v[116:117], v[116:117], v[132:133]
	v_lshlrev_b32_e32 v132, 16, v140
	v_and_b32_e32 v133, 0xffff0000, v140
	v_pk_mul_f32 v[118:119], v[118:119], v[134:135]
	v_lshlrev_b32_e32 v134, 16, v141
	v_and_b32_e32 v135, 0xffff0000, v141
	v_pk_mul_f32 v[108:109], v[108:109], v[132:133]
	v_lshlrev_b32_e32 v132, 16, v144
	v_and_b32_e32 v133, 0xffff0000, v144
	v_lshlrev_b32_e32 v136, 16, v138
	v_and_b32_e32 v137, 0xffff0000, v138
	v_lshlrev_b32_e32 v138, 16, v139
	v_and_b32_e32 v139, 0xffff0000, v139
	v_pk_mul_f32 v[110:111], v[110:111], v[134:135]
	v_lshlrev_b32_e32 v134, 16, v145
	v_and_b32_e32 v135, 0xffff0000, v145
	v_pk_mul_f32 v[104:105], v[104:105], v[132:133]
	v_lshlrev_b32_e32 v132, 16, v148
	v_and_b32_e32 v133, 0xffff0000, v148
	v_pk_mul_f32 v[122:123], v[122:123], v[138:139]
	v_pk_mul_f32 v[120:121], v[120:121], v[136:137]
	v_lshlrev_b32_e32 v136, 16, v142
	v_and_b32_e32 v137, 0xffff0000, v142
	v_lshlrev_b32_e32 v138, 16, v143
	v_and_b32_e32 v139, 0xffff0000, v143
	v_pk_mul_f32 v[106:107], v[106:107], v[134:135]
	v_lshlrev_b32_e32 v134, 16, v149
	v_and_b32_e32 v135, 0xffff0000, v149
	v_pk_mul_f32 v[96:97], v[96:97], v[132:133]
	v_lshlrev_b32_e32 v132, 16, v182
	v_and_b32_e32 v133, 0xffff0000, v182
	v_pk_mul_f32 v[114:115], v[114:115], v[138:139]
	v_pk_mul_f32 v[112:113], v[112:113], v[136:137]
	v_lshlrev_b32_e32 v136, 16, v146
	v_and_b32_e32 v137, 0xffff0000, v146
	v_lshlrev_b32_e32 v138, 16, v147
	v_and_b32_e32 v139, 0xffff0000, v147
	v_pk_mul_f32 v[98:99], v[98:99], v[134:135]
	v_lshlrev_b32_e32 v134, 16, v183
	v_and_b32_e32 v135, 0xffff0000, v183
	v_pk_mul_f32 v[88:89], v[88:89], v[132:133]
	v_lshlrev_b32_e32 v132, 16, v186
	v_and_b32_e32 v133, 0xffff0000, v186
	v_pk_mul_f32 v[102:103], v[102:103], v[138:139]
	v_pk_mul_f32 v[100:101], v[100:101], v[136:137]
	v_lshlrev_b32_e32 v136, 16, v150
	v_and_b32_e32 v137, 0xffff0000, v150
	v_lshlrev_b32_e32 v138, 16, v151
	v_and_b32_e32 v139, 0xffff0000, v151
	v_pk_mul_f32 v[90:91], v[90:91], v[134:135]
	v_lshlrev_b32_e32 v134, 16, v187
	v_and_b32_e32 v135, 0xffff0000, v187
	v_pk_mul_f32 v[80:81], v[80:81], v[132:133]
	v_lshlrev_b32_e32 v132, 16, v196
	v_and_b32_e32 v133, 0xffff0000, v196
	v_pk_mul_f32 v[94:95], v[94:95], v[138:139]
	v_pk_mul_f32 v[92:93], v[92:93], v[136:137]
	v_lshlrev_b32_e32 v136, 16, v184
	v_and_b32_e32 v137, 0xffff0000, v184
	v_lshlrev_b32_e32 v138, 16, v185
	v_and_b32_e32 v139, 0xffff0000, v185
	v_pk_mul_f32 v[82:83], v[82:83], v[134:135]
	v_lshlrev_b32_e32 v134, 16, v197
	v_and_b32_e32 v135, 0xffff0000, v197
	v_pk_mul_f32 v[72:73], v[72:73], v[132:133]
	v_lshl_add_u64 v[132:133], v[2:3], 0, s[48:49]
	v_pk_mul_f32 v[86:87], v[86:87], v[138:139]
	v_pk_mul_f32 v[84:85], v[84:85], v[136:137]
	v_lshlrev_b32_e32 v136, 16, v188
	v_and_b32_e32 v137, 0xffff0000, v188
	v_lshlrev_b32_e32 v138, 16, v189
	v_and_b32_e32 v139, 0xffff0000, v189
	v_pk_mul_f32 v[74:75], v[74:75], v[134:135]
	s_nop 0
	s_mov_b64 s[48:49], 0x90000
	v_pk_mul_f32 v[78:79], v[78:79], v[138:139]
	v_pk_mul_f32 v[76:77], v[76:77], v[136:137]
	v_lshlrev_b32_e32 v136, 16, v198
	v_and_b32_e32 v137, 0xffff0000, v198
	v_lshlrev_b32_e32 v138, 16, v199
	v_and_b32_e32 v139, 0xffff0000, v199
	v_lshl_add_u64 v[140:141], v[2:3], 0, s[48:49]
	v_pk_mul_f32 v[70:71], v[70:71], v[138:139]
	v_pk_mul_f32 v[68:69], v[68:69], v[136:137]
	s_nop 0
	s_mov_b64 s[48:49], 0xa0000
	v_lshl_add_u64 v[182:183], v[2:3], 0, s[48:49]
	s_nop 0
	s_mov_b64 s[48:49], 0xb0000
	v_lshl_add_u64 v[2:3], v[2:3], 0, s[48:49]
	v_pk_mul_f32 v[124:125], v[124:125], v[190:191]
	v_pk_mul_f32 v[128:129], v[128:129], v[208:209]
	s_waitcnt vmcnt(0)
	v_mov_b64_e32 v[144:145], v[212:213]
	v_mov_b64_e32 v[146:147], v[214:215]
	v_mov_b64_e32 v[132:133], v[216:217]
	v_mov_b64_e32 v[134:135], v[218:219]
	v_mov_b64_e32 v[136:137], v[220:221]
	v_mov_b64_e32 v[138:139], v[222:223]
	v_mov_b64_e32 v[140:141], v[224:225]
	v_mov_b64_e32 v[142:143], v[226:227]
	v_mov_b64_e32 v[148:149], v[228:229]
	v_mov_b64_e32 v[150:151], v[230:231]
	v_mov_b64_e32 v[182:183], v[232:233]
	v_mov_b64_e32 v[184:185], v[234:235]
	v_mov_b64_e32 v[186:187], v[236:237]
	v_mov_b64_e32 v[188:189], v[238:239]
	v_mov_b64_e32 v[196:197], v[240:241]
	v_mov_b64_e32 v[198:199], v[242:243]
	v_lshlrev_b32_e32 v2, 16, v144
	v_and_b32_e32 v3, 0xffff0000, v144
	v_lshlrev_b32_e32 v144, 16, v145
	v_and_b32_e32 v145, 0xffff0000, v145
	v_pk_mul_f32 v[66:67], v[66:67], v[144:145]
	v_pk_mul_f32 v[64:65], v[64:65], v[2:3]
	v_lshlrev_b32_e32 v2, 16, v132
	v_and_b32_e32 v3, 0xffff0000, v132
	v_lshlrev_b32_e32 v132, 16, v133
	v_and_b32_e32 v133, 0xffff0000, v133
	v_lshlrev_b32_e32 v144, 16, v134
	v_and_b32_e32 v145, 0xffff0000, v134
	v_lshlrev_b32_e32 v134, 16, v135
	v_and_b32_e32 v135, 0xffff0000, v135
	v_pk_mul_f32 v[58:59], v[58:59], v[132:133]
	v_pk_mul_f32 v[56:57], v[56:57], v[2:3]
	v_pk_mul_f32 v[54:55], v[54:55], v[134:135]
	v_lshlrev_b32_e32 v2, 16, v136
	v_and_b32_e32 v3, 0xffff0000, v136
	v_lshlrev_b32_e32 v132, 16, v137
	v_and_b32_e32 v133, 0xffff0000, v137
	v_lshlrev_b32_e32 v134, 16, v138
	v_and_b32_e32 v135, 0xffff0000, v138
	v_lshlrev_b32_e32 v136, 16, v139
	v_and_b32_e32 v137, 0xffff0000, v139
	v_pk_mul_f32 v[50:51], v[50:51], v[132:133]
	v_pk_mul_f32 v[48:49], v[48:49], v[2:3]
	v_pk_mul_f32 v[46:47], v[46:47], v[136:137]
	v_pk_mul_f32 v[44:45], v[44:45], v[134:135]
	v_lshlrev_b32_e32 v2, 16, v140
	v_and_b32_e32 v3, 0xffff0000, v140
	v_lshlrev_b32_e32 v132, 16, v141
	v_and_b32_e32 v133, 0xffff0000, v141
	v_lshlrev_b32_e32 v134, 16, v142
	v_and_b32_e32 v135, 0xffff0000, v142
	v_lshlrev_b32_e32 v136, 16, v143
	v_and_b32_e32 v137, 0xffff0000, v143
	v_pk_mul_f32 v[42:43], v[42:43], v[132:133]
	v_pk_mul_f32 v[40:41], v[40:41], v[2:3]
	v_pk_mul_f32 v[38:39], v[38:39], v[136:137]
	v_pk_mul_f32 v[36:37], v[36:37], v[134:135]
	v_lshlrev_b32_e32 v2, 16, v148
	v_and_b32_e32 v3, 0xffff0000, v148
	v_lshlrev_b32_e32 v132, 16, v149
	v_and_b32_e32 v133, 0xffff0000, v149
	v_lshlrev_b32_e32 v134, 16, v150
	v_and_b32_e32 v135, 0xffff0000, v150
	v_lshlrev_b32_e32 v136, 16, v151
	v_and_b32_e32 v137, 0xffff0000, v151
	v_pk_mul_f32 v[34:35], v[34:35], v[132:133]
	v_pk_mul_f32 v[32:33], v[32:33], v[2:3]
	v_pk_mul_f32 v[30:31], v[30:31], v[136:137]
	v_pk_mul_f32 v[28:29], v[28:29], v[134:135]
	v_lshlrev_b32_e32 v2, 16, v182
	v_and_b32_e32 v3, 0xffff0000, v182
	v_lshlrev_b32_e32 v132, 16, v183
	v_and_b32_e32 v133, 0xffff0000, v183
	v_lshlrev_b32_e32 v134, 16, v184
	v_and_b32_e32 v135, 0xffff0000, v184
	v_lshlrev_b32_e32 v136, 16, v185
	v_and_b32_e32 v137, 0xffff0000, v185
	v_pk_mul_f32 v[26:27], v[26:27], v[132:133]
	v_pk_mul_f32 v[24:25], v[24:25], v[2:3]
	v_pk_mul_f32 v[22:23], v[22:23], v[136:137]
	v_pk_mul_f32 v[20:21], v[20:21], v[134:135]
	v_lshlrev_b32_e32 v2, 16, v186
	v_and_b32_e32 v3, 0xffff0000, v186
	v_lshlrev_b32_e32 v132, 16, v187
	v_and_b32_e32 v133, 0xffff0000, v187
	v_lshlrev_b32_e32 v134, 16, v188
	v_and_b32_e32 v135, 0xffff0000, v188
	v_lshlrev_b32_e32 v136, 16, v189
	v_and_b32_e32 v137, 0xffff0000, v189
	v_lshlrev_b32_e32 v190, 16, v146
	v_and_b32_e32 v191, 0xffff0000, v146
	v_lshlrev_b32_e32 v146, 16, v147
	v_and_b32_e32 v147, 0xffff0000, v147
	v_pk_mul_f32 v[18:19], v[18:19], v[132:133]
	v_pk_mul_f32 v[16:17], v[16:17], v[2:3]
	v_pk_mul_f32 v[14:15], v[14:15], v[136:137]
	v_pk_mul_f32 v[12:13], v[12:13], v[134:135]
	v_lshlrev_b32_e32 v2, 16, v196
	v_and_b32_e32 v3, 0xffff0000, v196
	v_lshlrev_b32_e32 v132, 16, v197
	v_and_b32_e32 v133, 0xffff0000, v197
	v_lshlrev_b32_e32 v134, 16, v198
	v_and_b32_e32 v135, 0xffff0000, v198
	v_lshlrev_b32_e32 v136, 16, v199
	v_and_b32_e32 v137, 0xffff0000, v199
	v_pk_mul_f32 v[62:63], v[62:63], v[146:147]
	v_pk_mul_f32 v[60:61], v[60:61], v[190:191]
	v_pk_mul_f32 v[52:53], v[52:53], v[144:145]
	v_pk_mul_f32 v[10:11], v[10:11], v[132:133]
	v_pk_mul_f32 v[8:9], v[8:9], v[2:3]
	v_pk_mul_f32 v[6:7], v[6:7], v[136:137]
	v_pk_mul_f32 v[4:5], v[4:5], v[134:135]

.LBB0_136:
	s_lshl_b32 s0, s98, 8
	v_mov_b32_e32 v1, v192
	v_mov_b32_e32 v2, v169
	s_add_i32 s0, s0, s82
	s_and_b64 vcc, exec, s[36:37]
	v_add_u32_e32 v182, s0, v1
	s_lshl_b32 s0, s97, 8
	s_or_b32 s0, s0, s83
	v_lshl_add_u32 v2, v2, 3, s0
	v_ashrrev_i32_e32 v3, 31, v2
	v_lshlrev_b64 v[2:3], 1, v[2:3]
	v_ashrrev_i32_e32 v183, 31, v182
	v_lshl_add_u64 v[184:185], s[10:11], 0, v[2:3]
	v_lshlrev_b64 v[132:133], 12, v[182:183]
	v_lshl_add_u64 v[132:133], v[184:185], 0, v[132:133]
	global_load_dwordx4 v[196:199], v[132:133], off
	global_load_dwordx4 v[208:211], v[132:133], off offset:256
	v_add_u32_e32 v190, 16, v182
	v_ashrrev_i32_e32 v191, 31, v190
	v_lshlrev_b64 v[132:133], 12, v[190:191]
	v_lshl_add_u64 v[132:133], v[184:185], 0, v[132:133]
	global_load_dwordx4 v[152:155], v[132:133], off
	global_load_dwordx4 v[148:151], v[132:133], off offset:256
	v_add_u32_e32 v188, 32, v182
	v_ashrrev_i32_e32 v189, 31, v188
	v_lshlrev_b64 v[132:133], 12, v[188:189]
	v_lshl_add_u64 v[132:133], v[184:185], 0, v[132:133]
	global_load_dwordx4 v[144:147], v[132:133], off
	global_load_dwordx4 v[140:143], v[132:133], off offset:256
	v_add_u32_e32 v186, 48, v182
	v_ashrrev_i32_e32 v187, 31, v186
	v_lshlrev_b64 v[132:133], 12, v[186:187]
	v_lshl_add_u64 v[132:133], v[184:185], 0, v[132:133]
	global_load_dwordx4 v[136:139], v[132:133], off
	s_nop 0
	global_load_dwordx4 v[132:135], v[132:133], off offset:256
	v_lshlrev_b32_e32 v250, 12, v182
	v_mov_b32_e32 v251, v0
	v_lshl_add_u64 v[250:251], v[184:185], 0, v[250:251]
	s_mov_b64 s[48:49], 0x80000
	v_lshl_add_u64 v[250:251], v[250:251], 0, s[48:49]
	global_load_dwordx4 v[218:221], v[250:251], off
	global_load_dwordx4 v[222:225], v[250:251], off offset:256
	s_mov_b64 s[48:49], 0x10000
	v_lshl_add_u64 v[250:251], v[250:251], 0, s[48:49]
	global_load_dwordx4 v[226:229], v[250:251], off
	global_load_dwordx4 v[230:233], v[250:251], off offset:256
	v_lshl_add_u64 v[250:251], v[250:251], 0, s[48:49]
	global_load_dwordx4 v[234:237], v[250:251], off
	global_load_dwordx4 v[238:241], v[250:251], off offset:256
	v_lshl_add_u64 v[250:251], v[250:251], 0, s[48:49]
	global_load_dwordx4 v[242:245], v[250:251], off
	global_load_dwordx4 v[246:249], v[250:251], off offset:256
	v_lshlrev_b64 v[212:213], 11, v[182:183]
	s_mov_b64 s[0:1], -1
	s_waitcnt vmcnt(8)
	v_lshlrev_b32_e32 v214, 16, v196
	v_and_b32_e32 v215, 0xffff0000, v196
	v_lshlrev_b32_e32 v196, 16, v197
	v_and_b32_e32 v197, 0xffff0000, v197
	v_lshlrev_b32_e32 v216, 16, v198
	v_and_b32_e32 v217, 0xffff0000, v198
	v_lshlrev_b32_e32 v198, 16, v199
	v_and_b32_e32 v199, 0xffff0000, v199
	v_pk_mul_f32 v[126:127], v[126:127], v[196:197]
	v_pk_mul_f32 v[124:125], v[124:125], v[214:215]
	v_pk_mul_f32 v[128:129], v[128:129], v[216:217]
	v_pk_mul_f32 v[130:131], v[130:131], v[198:199]
	v_cvt_pk_bf16_f32 v124, v124, v125
	v_cvt_pk_bf16_f32 v125, v126, v127
	v_cvt_pk_bf16_f32 v126, v128, v129
	v_lshl_add_u64 v[128:129], s[6:7], 0, v[212:213]
	v_cvt_pk_bf16_f32 v127, v130, v131
	v_lshl_add_u64 v[128:129], v[128:129], 0, v[2:3]
	global_store_dwordx4 v[128:129], v[124:127], off sc1
	v_lshlrev_b32_e32 v130, 16, v210
	v_and_b32_e32 v131, 0xffff0000, v210
	v_lshlrev_b32_e32 v124, 16, v208
	v_and_b32_e32 v125, 0xffff0000, v208
	v_lshlrev_b32_e32 v126, 16, v209
	v_and_b32_e32 v127, 0xffff0000, v209
	v_lshlrev_b32_e32 v196, 16, v211
	v_and_b32_e32 v197, 0xffff0000, v211
	v_pk_mul_f32 v[118:119], v[118:119], v[126:127]
	v_pk_mul_f32 v[116:117], v[116:117], v[124:125]
	v_pk_mul_f32 v[122:123], v[122:123], v[196:197]
	v_pk_mul_f32 v[120:121], v[120:121], v[130:131]
	v_cvt_pk_bf16_f32 v116, v116, v117
	v_cvt_pk_bf16_f32 v117, v118, v119
	v_cvt_pk_bf16_f32 v118, v120, v121
	v_cvt_pk_bf16_f32 v119, v122, v123
	global_store_dwordx4 v[128:129], v[116:119], off offset:256 sc1
	v_lshlrev_b32_e32 v120, 16, v153
	v_and_b32_e32 v121, 0xffff0000, v153
	v_lshlrev_b32_e32 v118, 16, v152
	v_and_b32_e32 v119, 0xffff0000, v152
	v_lshlrev_b32_e32 v122, 16, v154
	v_and_b32_e32 v123, 0xffff0000, v154
	v_lshlrev_b64 v[116:117], 11, v[190:191]
	v_lshlrev_b32_e32 v124, 16, v155
	v_and_b32_e32 v125, 0xffff0000, v155
	v_pk_mul_f32 v[110:111], v[110:111], v[120:121]
	v_pk_mul_f32 v[108:109], v[108:109], v[118:119]
	v_pk_mul_f32 v[112:113], v[112:113], v[122:123]
	v_pk_mul_f32 v[114:115], v[114:115], v[124:125]
	v_cvt_pk_bf16_f32 v108, v108, v109
	v_cvt_pk_bf16_f32 v109, v110, v111
	v_cvt_pk_bf16_f32 v110, v112, v113
	v_lshl_add_u64 v[112:113], s[6:7], 0, v[116:117]
	v_cvt_pk_bf16_f32 v111, v114, v115
	v_lshl_add_u64 v[112:113], v[112:113], 0, v[2:3]
	global_store_dwordx4 v[112:113], v[108:111], off sc1
	v_lshlrev_b32_e32 v114, 16, v150
	v_and_b32_e32 v115, 0xffff0000, v150
	v_lshlrev_b32_e32 v108, 16, v148
	v_and_b32_e32 v109, 0xffff0000, v148
	v_lshlrev_b32_e32 v110, 16, v149
	v_and_b32_e32 v111, 0xffff0000, v149
	v_lshlrev_b32_e32 v116, 16, v151
	v_and_b32_e32 v117, 0xffff0000, v151
	v_pk_mul_f32 v[106:107], v[106:107], v[110:111]
	v_pk_mul_f32 v[104:105], v[104:105], v[108:109]
	v_pk_mul_f32 v[108:109], v[102:103], v[116:117]
	v_pk_mul_f32 v[102:103], v[100:101], v[114:115]
	v_cvt_pk_bf16_f32 v100, v104, v105
	v_cvt_pk_bf16_f32 v101, v106, v107
	v_cvt_pk_bf16_f32 v102, v102, v103
	v_cvt_pk_bf16_f32 v103, v108, v109
	global_store_dwordx4 v[112:113], v[100:103], off offset:256 sc1
	v_lshlrev_b32_e32 v104, 16, v145
	v_and_b32_e32 v105, 0xffff0000, v145
	v_lshlrev_b32_e32 v102, 16, v144
	v_and_b32_e32 v103, 0xffff0000, v144
	v_lshlrev_b64 v[100:101], 11, v[188:189]
	v_lshlrev_b32_e32 v106, 16, v146
	v_and_b32_e32 v107, 0xffff0000, v146
	v_lshlrev_b32_e32 v108, 16, v147
	v_and_b32_e32 v109, 0xffff0000, v147
	v_pk_mul_f32 v[96:97], v[96:97], v[102:103]
	v_pk_mul_f32 v[98:99], v[98:99], v[104:105]
	v_pk_mul_f32 v[102:103], v[94:95], v[108:109]
	v_pk_mul_f32 v[94:95], v[92:93], v[106:107]
	v_cvt_pk_bf16_f32 v92, v96, v97
	v_lshl_add_u64 v[96:97], s[6:7], 0, v[100:101]
	v_cvt_pk_bf16_f32 v93, v98, v99
	v_cvt_pk_bf16_f32 v94, v94, v95
	v_cvt_pk_bf16_f32 v95, v102, v103
	v_lshl_add_u64 v[96:97], v[96:97], 0, v[2:3]
	global_store_dwordx4 v[96:97], v[92:95], off sc1
	v_lshlrev_b32_e32 v98, 16, v142
	v_and_b32_e32 v99, 0xffff0000, v142
	v_lshlrev_b32_e32 v92, 16, v140
	v_and_b32_e32 v93, 0xffff0000, v140
	v_lshlrev_b32_e32 v94, 16, v141
	v_and_b32_e32 v95, 0xffff0000, v141
	v_lshlrev_b32_e32 v100, 16, v143
	v_and_b32_e32 v101, 0xffff0000, v143
	v_pk_mul_f32 v[90:91], v[90:91], v[94:95]
	v_pk_mul_f32 v[88:89], v[88:89], v[92:93]
	v_pk_mul_f32 v[92:93], v[86:87], v[100:101]
	v_pk_mul_f32 v[86:87], v[84:85], v[98:99]
	v_cvt_pk_bf16_f32 v84, v88, v89
	v_cvt_pk_bf16_f32 v85, v90, v91
	v_cvt_pk_bf16_f32 v86, v86, v87
	v_cvt_pk_bf16_f32 v87, v92, v93
	global_store_dwordx4 v[96:97], v[84:87], off offset:256 sc1
	v_lshlrev_b32_e32 v88, 16, v137
	v_and_b32_e32 v89, 0xffff0000, v137
	v_lshlrev_b32_e32 v86, 16, v136
	v_and_b32_e32 v87, 0xffff0000, v136
	v_lshlrev_b64 v[84:85], 11, v[186:187]
	v_lshlrev_b32_e32 v90, 16, v138
	v_and_b32_e32 v91, 0xffff0000, v138
	v_lshlrev_b32_e32 v92, 16, v139
	v_and_b32_e32 v93, 0xffff0000, v139
	v_pk_mul_f32 v[80:81], v[80:81], v[86:87]
	v_pk_mul_f32 v[82:83], v[82:83], v[88:89]
	v_pk_mul_f32 v[86:87], v[78:79], v[92:93]
	v_pk_mul_f32 v[78:79], v[76:77], v[90:91]
	v_cvt_pk_bf16_f32 v76, v80, v81
	v_lshl_add_u64 v[80:81], s[6:7], 0, v[84:85]
	v_cvt_pk_bf16_f32 v77, v82, v83
	v_cvt_pk_bf16_f32 v78, v78, v79
	v_cvt_pk_bf16_f32 v79, v86, v87
	v_lshl_add_u64 v[80:81], v[80:81], 0, v[2:3]
	global_store_dwordx4 v[80:81], v[76:79], off sc1
	v_lshlrev_b32_e32 v82, 16, v134
	v_and_b32_e32 v83, 0xffff0000, v134
	v_lshlrev_b32_e32 v76, 16, v132
	v_and_b32_e32 v77, 0xffff0000, v132
	v_lshlrev_b32_e32 v78, 16, v133
	v_and_b32_e32 v79, 0xffff0000, v133
	v_lshlrev_b32_e32 v84, 16, v135
	v_and_b32_e32 v85, 0xffff0000, v135
	v_pk_mul_f32 v[74:75], v[74:75], v[78:79]
	v_pk_mul_f32 v[72:73], v[72:73], v[76:77]
	v_pk_mul_f32 v[76:77], v[70:71], v[84:85]
	v_pk_mul_f32 v[70:71], v[68:69], v[82:83]
	v_add_u32_e32 v100, 0x80, v182
	v_cvt_pk_bf16_f32 v68, v72, v73
	v_cvt_pk_bf16_f32 v69, v74, v75
	v_cvt_pk_bf16_f32 v70, v70, v71
	v_cvt_pk_bf16_f32 v71, v76, v77
	v_ashrrev_i32_e32 v101, 31, v100
	global_store_dwordx4 v[80:81], v[68:71], off offset:256 sc1
	v_add_u32_e32 v102, 0x90, v182
	v_ashrrev_i32_e32 v103, 31, v102
	v_lshlrev_b64 v[68:69], 12, v[100:101]
	v_lshl_add_u64 v[68:69], v[184:185], 0, v[68:69]
	v_lshlrev_b64 v[68:69], 12, v[102:103]
	v_lshl_add_u64 v[68:69], v[184:185], 0, v[68:69]
	v_add_u32_e32 v104, 0xa0, v182
	v_ashrrev_i32_e32 v105, 31, v104
	v_lshlrev_b64 v[68:69], 12, v[104:105]
	v_lshl_add_u64 v[68:69], v[184:185], 0, v[68:69]
	v_add_u32_e32 v106, 0xb0, v182
	v_ashrrev_i32_e32 v107, 31, v106
	v_lshlrev_b64 v[68:69], 12, v[106:107]
	v_lshl_add_u64 v[68:69], v[184:185], 0, v[68:69]
	s_nop 0
	v_lshlrev_b64 v[100:101], 11, v[100:101]
	s_waitcnt vmcnt(0)
	v_mov_b64_e32 v[72:73], v[218:219]
	v_mov_b64_e32 v[74:75], v[220:221]
	v_mov_b64_e32 v[76:77], v[222:223]
	v_mov_b64_e32 v[78:79], v[224:225]
	v_mov_b64_e32 v[80:81], v[226:227]
	v_mov_b64_e32 v[82:83], v[228:229]
	v_mov_b64_e32 v[84:85], v[230:231]
	v_mov_b64_e32 v[86:87], v[232:233]
	v_mov_b64_e32 v[88:89], v[234:235]
	v_mov_b64_e32 v[90:91], v[236:237]
	v_mov_b64_e32 v[92:93], v[238:239]
	v_mov_b64_e32 v[94:95], v[240:241]
	v_mov_b64_e32 v[96:97], v[242:243]
	v_mov_b64_e32 v[98:99], v[244:245]
	v_mov_b64_e32 v[68:69], v[246:247]
	v_mov_b64_e32 v[70:71], v[248:249]
	v_lshlrev_b32_e32 v108, 16, v72
	v_and_b32_e32 v109, 0xffff0000, v72
	v_lshlrev_b32_e32 v72, 16, v73
	v_and_b32_e32 v73, 0xffff0000, v73
	v_lshlrev_b32_e32 v110, 16, v74
	v_and_b32_e32 v111, 0xffff0000, v74
	v_lshlrev_b32_e32 v74, 16, v75
	v_and_b32_e32 v75, 0xffff0000, v75
	v_pk_mul_f32 v[64:65], v[64:65], v[108:109]
	v_pk_mul_f32 v[66:67], v[66:67], v[72:73]
	v_pk_mul_f32 v[72:73], v[62:63], v[74:75]
	v_pk_mul_f32 v[62:63], v[60:61], v[110:111]
	v_cvt_pk_bf16_f32 v60, v64, v65
	v_lshl_add_u64 v[64:65], s[6:7], 0, v[100:101]
	v_cvt_pk_bf16_f32 v61, v66, v67
	v_cvt_pk_bf16_f32 v62, v62, v63
	v_cvt_pk_bf16_f32 v63, v72, v73
	v_lshl_add_u64 v[64:65], v[64:65], 0, v[2:3]
	global_store_dwordx4 v[64:65], v[60:63], off sc1
	v_lshlrev_b32_e32 v66, 16, v78
	v_and_b32_e32 v67, 0xffff0000, v78
	v_lshlrev_b32_e32 v60, 16, v76
	v_and_b32_e32 v61, 0xffff0000, v76
	v_lshlrev_b32_e32 v62, 16, v77
	v_and_b32_e32 v63, 0xffff0000, v77
	v_lshlrev_b32_e32 v72, 16, v79
	v_and_b32_e32 v73, 0xffff0000, v79
	v_pk_mul_f32 v[58:59], v[58:59], v[62:63]
	v_pk_mul_f32 v[56:57], v[56:57], v[60:61]
	v_pk_mul_f32 v[60:61], v[54:55], v[72:73]
	v_pk_mul_f32 v[54:55], v[52:53], v[66:67]
	v_cvt_pk_bf16_f32 v52, v56, v57
	v_cvt_pk_bf16_f32 v53, v58, v59
	v_cvt_pk_bf16_f32 v54, v54, v55
	v_cvt_pk_bf16_f32 v55, v60, v61
	global_store_dwordx4 v[64:65], v[52:55], off offset:256 sc1
	v_lshlrev_b32_e32 v56, 16, v81
	v_and_b32_e32 v57, 0xffff0000, v81
	v_lshlrev_b32_e32 v54, 16, v80
	v_and_b32_e32 v55, 0xffff0000, v80
	v_lshlrev_b64 v[52:53], 11, v[102:103]
	v_lshlrev_b32_e32 v58, 16, v82
	v_and_b32_e32 v59, 0xffff0000, v82
	v_lshlrev_b32_e32 v60, 16, v83
	v_and_b32_e32 v61, 0xffff0000, v83
	v_pk_mul_f32 v[48:49], v[48:49], v[54:55]
	v_pk_mul_f32 v[50:51], v[50:51], v[56:57]
	v_pk_mul_f32 v[54:55], v[46:47], v[60:61]
	v_pk_mul_f32 v[46:47], v[44:45], v[58:59]
	v_cvt_pk_bf16_f32 v44, v48, v49
	v_lshl_add_u64 v[48:49], s[6:7], 0, v[52:53]
	v_cvt_pk_bf16_f32 v45, v50, v51
	v_cvt_pk_bf16_f32 v46, v46, v47
	v_cvt_pk_bf16_f32 v47, v54, v55
	v_lshl_add_u64 v[48:49], v[48:49], 0, v[2:3]
	global_store_dwordx4 v[48:49], v[44:47], off sc1
	v_lshlrev_b32_e32 v50, 16, v86
	v_and_b32_e32 v51, 0xffff0000, v86
	v_lshlrev_b32_e32 v44, 16, v84
	v_and_b32_e32 v45, 0xffff0000, v84
	v_lshlrev_b32_e32 v46, 16, v85
	v_and_b32_e32 v47, 0xffff0000, v85
	v_lshlrev_b32_e32 v52, 16, v87
	v_and_b32_e32 v53, 0xffff0000, v87
	v_pk_mul_f32 v[42:43], v[42:43], v[46:47]
	v_pk_mul_f32 v[40:41], v[40:41], v[44:45]
	v_pk_mul_f32 v[44:45], v[38:39], v[52:53]
	v_pk_mul_f32 v[38:39], v[36:37], v[50:51]
	v_cvt_pk_bf16_f32 v36, v40, v41
	v_cvt_pk_bf16_f32 v37, v42, v43
	v_cvt_pk_bf16_f32 v38, v38, v39
	v_cvt_pk_bf16_f32 v39, v44, v45
	global_store_dwordx4 v[48:49], v[36:39], off offset:256 sc1
	v_lshlrev_b32_e32 v40, 16, v89
	v_and_b32_e32 v41, 0xffff0000, v89
	v_lshlrev_b32_e32 v38, 16, v88
	v_and_b32_e32 v39, 0xffff0000, v88
	v_lshlrev_b64 v[36:37], 11, v[104:105]
	v_lshlrev_b32_e32 v42, 16, v90
	v_and_b32_e32 v43, 0xffff0000, v90
	v_lshlrev_b32_e32 v44, 16, v91
	v_and_b32_e32 v45, 0xffff0000, v91
	v_pk_mul_f32 v[32:33], v[32:33], v[38:39]
	v_pk_mul_f32 v[34:35], v[34:35], v[40:41]
	v_pk_mul_f32 v[38:39], v[30:31], v[44:45]
	v_pk_mul_f32 v[30:31], v[28:29], v[42:43]
	v_cvt_pk_bf16_f32 v28, v32, v33
	v_lshl_add_u64 v[32:33], s[6:7], 0, v[36:37]
	v_cvt_pk_bf16_f32 v29, v34, v35
	v_cvt_pk_bf16_f32 v30, v30, v31
	v_cvt_pk_bf16_f32 v31, v38, v39
	v_lshl_add_u64 v[32:33], v[32:33], 0, v[2:3]
	global_store_dwordx4 v[32:33], v[28:31], off sc1
	v_lshlrev_b32_e32 v34, 16, v94
	v_and_b32_e32 v35, 0xffff0000, v94
	v_lshlrev_b32_e32 v28, 16, v92
	v_and_b32_e32 v29, 0xffff0000, v92
	v_lshlrev_b32_e32 v30, 16, v93
	v_and_b32_e32 v31, 0xffff0000, v93
	v_lshlrev_b32_e32 v36, 16, v95
	v_and_b32_e32 v37, 0xffff0000, v95
	v_pk_mul_f32 v[26:27], v[26:27], v[30:31]
	v_pk_mul_f32 v[24:25], v[24:25], v[28:29]
	v_pk_mul_f32 v[28:29], v[22:23], v[36:37]
	v_pk_mul_f32 v[22:23], v[20:21], v[34:35]
	v_cvt_pk_bf16_f32 v20, v24, v25
	v_cvt_pk_bf16_f32 v21, v26, v27
	v_cvt_pk_bf16_f32 v22, v22, v23
	v_cvt_pk_bf16_f32 v23, v28, v29
	global_store_dwordx4 v[32:33], v[20:23], off offset:256 sc1
	v_lshlrev_b32_e32 v24, 16, v97
	v_and_b32_e32 v25, 0xffff0000, v97
	v_lshlrev_b32_e32 v22, 16, v96
	v_and_b32_e32 v23, 0xffff0000, v96
	v_lshlrev_b64 v[20:21], 11, v[106:107]
	v_lshlrev_b32_e32 v26, 16, v98
	v_and_b32_e32 v27, 0xffff0000, v98
	v_lshlrev_b32_e32 v28, 16, v99
	v_and_b32_e32 v29, 0xffff0000, v99
	v_pk_mul_f32 v[16:17], v[16:17], v[22:23]
	v_pk_mul_f32 v[18:19], v[18:19], v[24:25]
	v_pk_mul_f32 v[22:23], v[14:15], v[28:29]
	v_pk_mul_f32 v[14:15], v[12:13], v[26:27]
	v_cvt_pk_bf16_f32 v12, v16, v17
	v_lshl_add_u64 v[16:17], s[6:7], 0, v[20:21]
	v_cvt_pk_bf16_f32 v13, v18, v19
	v_cvt_pk_bf16_f32 v14, v14, v15
	v_cvt_pk_bf16_f32 v15, v22, v23
	v_lshl_add_u64 v[16:17], v[16:17], 0, v[2:3]
	global_store_dwordx4 v[16:17], v[12:15], off sc1
	v_lshlrev_b32_e32 v2, 16, v68
	v_and_b32_e32 v3, 0xffff0000, v68
	v_lshlrev_b32_e32 v12, 16, v69
	v_and_b32_e32 v13, 0xffff0000, v69
	v_lshlrev_b32_e32 v14, 16, v70
	v_and_b32_e32 v15, 0xffff0000, v70
	v_lshlrev_b32_e32 v18, 16, v71
	v_and_b32_e32 v19, 0xffff0000, v71
	v_pk_mul_f32 v[10:11], v[10:11], v[12:13]
	v_pk_mul_f32 v[2:3], v[8:9], v[2:3]
	v_pk_mul_f32 v[6:7], v[6:7], v[18:19]
	v_pk_mul_f32 v[4:5], v[4:5], v[14:15]
	v_cvt_pk_bf16_f32 v2, v2, v3
	v_cvt_pk_bf16_f32 v3, v10, v11
	v_cvt_pk_bf16_f32 v4, v4, v5
	v_cvt_pk_bf16_f32 v5, v6, v7
	global_store_dwordx4 v[16:17], v[2:5], off offset:256 sc1
	s_cbranch_vccnz .LBB0_118
	v_readlane_b32 s0, v252, 41
	v_readlane_b32 s1, v252, 42
	s_andn2_b64 vcc, exec, s[0:1]
	s_cbranch_vccnz .LBB0_117
	s_barrier
	s_branch .LBB0_117
